# attention trip loop: loop-carried updates moved ahead of the trip-end barrier (back-edge rotation), on top of v148
# baseline (speedup 1.0000x reference)
; #define ATT_DMAK(t) do { const int sl_ = (t) % NSLOT; _Pragma("unroll") for (int i = 0; i < 2; ++i) \
;         __builtin_amdgcn_global_load_lds((const unsigned*)(Kg + (size_t)(t) * 16384 + i * 1024), (LAS unsigned*)(lds + OFF_K + sl_ * KBUF + wid * 2048 + i * 1024), 16, 0, 0); } while (0)
; #define ATT_DMAV(t) do { const int sl_ = (t) % NSLOT; _Pragma("unroll") for (int i = 0; i < 2; ++i) \
;         __builtin_amdgcn_global_load_lds((const unsigned*)(Vg + (size_t)(t) * 16384 + i * 1024), (LAS unsigned*)(lds + OFF_V + sl_ * VBUF + wid * 2048 + i * 1024), 16, 0, 0); } while (0)
; __device__ __forceinline__ void attn_unit(LAS unsigned char* lds, int b, int hh, int qb, const bf16_t* QK, const bf16_t* VT, bf16_t* CAT) {
;     ...
;     for (int t = 0; t <= nt; ++t) {
;         if (t + 2 < nt) ATT_DMAK(t + 2);
;         if (t + 1 < nt) ATT_DMAV(t + 1);
;         if (!lead && t >= 1) ATT_SOFTMAX(t - 1);
;         if (t >= 1) ATT_PV(t - 1);
;         if (t < nt) ATT_QK(t);
;         if (lead && t < nt) ATT_SOFTMAX(t);
;         if (t + 2 < nt) asm volatile("s_waitcnt vmcnt(4) lgkmcnt(0)" ::: "memory"); else asm volatile("s_waitcnt vmcnt(0) lgkmcnt(0)" ::: "memory");
;         __builtin_amdgcn_s_barrier(); asm volatile("" ::: "memory");
;     }
.LBB0_247:
	s_add_i32 s28, s28, 64
	s_add_i32 s26, s26, 1
	s_addk_i32 s53, 0x4000
	s_add_i32 s1, s1, 1
	s_add_i32 s58, s58, 1
	s_add_i32 s59, s59, 1
	v_add_u32_e32 v192, 0x100, v192
	v_add_u32_e32 v188, 0x100, v188
	v_lshl_add_u64 v[164:165], v[164:165], 0, s[74:75]
	v_lshl_add_u64 v[176:177], v[176:177], 0, s[74:75]
	s_cmp_lg_u32 s52, s53
	v_add_u32_e32 v189, 0x100, v189
	s_barrier
	s_cbranch_scc0 .LBB0_319

; #define ATT_DMAK(t) do { const int sl_ = (t) % NSLOT; _Pragma("unroll") for (int i = 0; i < 2; ++i) \
;         __builtin_amdgcn_global_load_lds((const unsigned*)(Kg + (size_t)(t) * 16384 + i * 1024), (LAS unsigned*)(lds + OFF_K + sl_ * KBUF + wid * 2048 + i * 1024), 16, 0, 0); } while (0)
; #define ATT_DMAV(t) do { const int sl_ = (t) % NSLOT; _Pragma("unroll") for (int i = 0; i < 2; ++i) \
;         __builtin_amdgcn_global_load_lds((const unsigned*)(Vg + (size_t)(t) * 16384 + i * 1024), (LAS unsigned*)(lds + OFF_V + sl_ * VBUF + wid * 2048 + i * 1024), 16, 0, 0); } while (0)
; __device__ __forceinline__ void attn_unit(LAS unsigned char* lds, int b, int hh, int qb, const bf16_t* QK, const bf16_t* VT, bf16_t* CAT) {
;     ...
;     for (int t = 0; t <= nt; ++t) {
;         if (t + 2 < nt) ATT_DMAK(t + 2);
;         if (t + 1 < nt) ATT_DMAV(t + 1);
;         if (!lead && t >= 1) ATT_SOFTMAX(t - 1);
;         if (t >= 1) ATT_PV(t - 1);
;         if (t < nt) ATT_QK(t);
;         if (lead && t < nt) ATT_SOFTMAX(t);
;         if (t + 2 < nt) asm volatile("s_waitcnt vmcnt(4) lgkmcnt(0)" ::: "memory"); else asm volatile("s_waitcnt vmcnt(0) lgkmcnt(0)" ::: "memory");
;         __builtin_amdgcn_s_barrier(); asm volatile("" ::: "memory");
;     }
.LBB0_390:
	s_add_i32 s27, s27, 64
	s_addk_i32 s48, 0x4000
	s_add_i32 s51, s51, 1
	s_add_i32 s59, s59, 1
	s_add_i32 s49, s49, 1
	v_add_u32_e32 v193, 0x100, v193
	v_add_u32_e32 v189, 0x100, v189
	v_lshl_add_u64 v[164:165], v[164:165], 0, s[74:75]
	v_lshl_add_u64 v[176:177], v[176:177], 0, s[74:75]
	s_cmp_lg_u32 s46, s66
	v_add_u32_e32 v190, 0x100, v190
	s_barrier
	s_cbranch_scc0 .LBB0_393
	s_mov_b32 s67, s66
	s_branch .LBB0_320

; #define ATT_DMAK(t) do { const int sl_ = (t) % NSLOT; _Pragma("unroll") for (int i = 0; i < 2; ++i) \
;         __builtin_amdgcn_global_load_lds((const unsigned*)(Kg + (size_t)(t) * 16384 + i * 1024), (LAS unsigned*)(lds + OFF_K + sl_ * KBUF + wid * 2048 + i * 1024), 16, 0, 0); } while (0)
; #define ATT_DMAV(t) do { const int sl_ = (t) % NSLOT; _Pragma("unroll") for (int i = 0; i < 2; ++i) \
;         __builtin_amdgcn_global_load_lds((const unsigned*)(Vg + (size_t)(t) * 16384 + i * 1024), (LAS unsigned*)(lds + OFF_V + sl_ * VBUF + wid * 2048 + i * 1024), 16, 0, 0); } while (0)
; __device__ __forceinline__ void attn_unit(LAS unsigned char* lds, int b, int hh, int qb, const bf16_t* QK, const bf16_t* VT, bf16_t* CAT) {
;     ...
;     for (int t = 0; t <= nt; ++t) {
;         if (t + 2 < nt) ATT_DMAK(t + 2);
;         if (t + 1 < nt) ATT_DMAV(t + 1);
;         if (!lead && t >= 1) ATT_SOFTMAX(t - 1);
;         if (t >= 1) ATT_PV(t - 1);
;         if (t < nt) ATT_QK(t);
;         if (lead && t < nt) ATT_SOFTMAX(t);
;         if (t + 2 < nt) asm volatile("s_waitcnt vmcnt(4) lgkmcnt(0)" ::: "memory"); else asm volatile("s_waitcnt vmcnt(0) lgkmcnt(0)" ::: "memory");
;         __builtin_amdgcn_s_barrier(); asm volatile("" ::: "memory");
;     }
.LBB0_394:
	s_add_i32 s28, s28, 64
	s_add_i32 s51, s51, 1
	s_addk_i32 s1, 0x4000
	s_add_i32 s48, s48, 1
	s_add_i32 s63, s63, 1
	s_add_i32 s66, s66, 1
	v_add_u32_e32 v193, 0x100, v193
	v_add_u32_e32 v189, 0x100, v189
	v_lshl_add_u64 v[164:165], v[164:165], 0, s[74:75]
	v_lshl_add_u64 v[176:177], v[176:177], 0, s[74:75]
	s_cmp_lg_u32 s46, s1
	v_add_u32_e32 v190, 0x100, v190
	s_barrier
	s_cbranch_scc0 .LBB0_466

; #define ATT_DMAK(t) do { const int sl_ = (t) % NSLOT; _Pragma("unroll") for (int i = 0; i < 2; ++i) \
;         __builtin_amdgcn_global_load_lds((const unsigned*)(Kg + (size_t)(t) * 16384 + i * 1024), (LAS unsigned*)(lds + OFF_K + sl_ * KBUF + wid * 2048 + i * 1024), 16, 0, 0); } while (0)
; #define ATT_DMAV(t) do { const int sl_ = (t) % NSLOT; _Pragma("unroll") for (int i = 0; i < 2; ++i) \
;         __builtin_amdgcn_global_load_lds((const unsigned*)(Vg + (size_t)(t) * 16384 + i * 1024), (LAS unsigned*)(lds + OFF_V + sl_ * VBUF + wid * 2048 + i * 1024), 16, 0, 0); } while (0)
; __device__ __forceinline__ void attn_unit(LAS unsigned char* lds, int b, int hh, int qb, const bf16_t* QK, const bf16_t* VT, bf16_t* CAT) {
;     ...
;     for (int t = 0; t <= nt; ++t) {
;         if (t + 2 < nt) ATT_DMAK(t + 2);
;         if (t + 1 < nt) ATT_DMAV(t + 1);
;         if (!lead && t >= 1) ATT_SOFTMAX(t - 1);
;         if (t >= 1) ATT_PV(t - 1);
;         if (t < nt) ATT_QK(t);
;         if (lead && t < nt) ATT_SOFTMAX(t);
;         if (t + 2 < nt) asm volatile("s_waitcnt vmcnt(4) lgkmcnt(0)" ::: "memory"); else asm volatile("s_waitcnt vmcnt(0) lgkmcnt(0)" ::: "memory");
;         __builtin_amdgcn_s_barrier(); asm volatile("" ::: "memory");
;     }
.LBB0_467:
	s_add_i32 s26, s26, 64
	s_add_i32 s46, s46, 1
	s_addk_i32 s48, 0x4000
	s_add_i32 s1, s1, 1
	s_add_i32 s49, s49, 1
	s_add_i32 s50, s50, 1
	v_add_u32_e32 v186, 0x100, v186
	v_add_u32_e32 v182, 0x100, v182
	v_lshl_add_u64 v[148:149], v[148:149], 0, s[74:75]
	v_lshl_add_u64 v[150:151], v[150:151], 0, s[74:75]
	s_cmp_lg_u32 s27, s48
	v_add_u32_e32 v183, 0x100, v183
	s_barrier
	s_cbranch_scc0 .LBB0_226
